# attention phases: one static s_setprio 1 for the waves of group 1 (reset at phase end) so the two waves per SIMD do not run their MFMA/VALU sections in lockstep
# baseline (speedup 1.0000x reference)
.LBB0_1041:
	s_or_b64 exec, exec, s[0:1]
	v_mov_b32_e32 v0, v205
	s_waitcnt lgkmcnt(0)
	s_barrier
	v_readlane_b32 s0, v250, 1
	v_and_b32_e32 v2, 63, v0
	v_lshlrev_b32_e32 v2, 2, v2
	global_load_dword v3, v2, s[78:79]
	global_load_dword v4, v2, s[78:79] offset:256
	v_readlane_b32 s1, v250, 2
	v_xor_b32_e32 v5, 32, v214
	v_readlane_b32 s2, v250, 3
	v_readlane_b32 s3, v250, 4
	v_readlane_b32 s4, v250, 5
	v_readlane_b32 s5, v250, 6
	v_readlane_b32 s6, v250, 7
	v_readlane_b32 s7, v250, 8
	s_waitcnt vmcnt(0)
	v_max_f32_e64 v3, |v3|, |v3|
	v_max_f32_e64 v4, |v4|, |v4|
	v_max_f32_e32 v3, v3, v4
	global_load_dword v4, v2, s[0:1]
	s_nop 0
	global_load_dword v2, v2, s[0:1] offset:256
	v_readfirstlane_b32 s0, v204
	s_lshr_b32 s0, s0, 8
	v_readlane_b32 s1, v250, 43
	s_add_i32 s14, s0, s1
	s_and_b32 s0, s14, 1
	s_bfe_u32 s1, s14, 0x30004
	s_lshl_b32 s1, s1, 1
	s_or_b32 s0, s0, s1
	s_bfe_u32 s1, s14, 0x10001
	s_lshl_b32 s1, s1, 6
	s_or_b32 s0, s0, s1
	s_bfe_u32 s1, s14, 0x20007
	s_lshl_b32 s1, s1, 4
	s_or_b32 s0, s0, s1
	s_bfe_u32 s1, s14, 0x20002
	s_lshl_b32 s1, s1, 7
	s_or_b32 s14, s0, s1
	s_bitcmp1_b32 s14, 0
	s_cbranch_scc0 .Lprio_skip_C
	s_setprio 1
.Lprio_skip_C:
	s_cmpk_lt_i32 s14, 0x200
	s_waitcnt vmcnt(1)
	v_max_f32_e64 v4, |v4|, |v4|
	s_waitcnt vmcnt(0)
	v_max_f32_e64 v2, |v2|, |v2|
	v_max_f32_e32 v2, v4, v2
	v_and_b32_e32 v4, 64, v214
	v_add_u32_e32 v4, 64, v4
	v_cmp_lt_i32_e32 vcc, v5, v4
	s_nop 1
	v_cndmask_b32_e32 v5, v214, v5, vcc
	v_lshlrev_b32_e32 v170, 2, v5
	ds_bpermute_b32 v5, v170, v3
	s_waitcnt lgkmcnt(0)
	v_max_f32_e32 v5, v5, v5
	v_max_f32_e32 v3, v3, v5
	ds_bpermute_b32 v5, v170, v2
	s_waitcnt lgkmcnt(0)
	v_max_f32_e32 v5, v5, v5
	v_max_f32_e32 v2, v2, v5
	v_xor_b32_e32 v5, 16, v214
	v_cmp_lt_i32_e32 vcc, v5, v4
	s_nop 1
	v_cndmask_b32_e32 v5, v214, v5, vcc
	v_lshlrev_b32_e32 v5, 2, v5
	ds_bpermute_b32 v6, v5, v3
	ds_bpermute_b32 v5, v5, v2
	s_waitcnt lgkmcnt(1)
	v_max_f32_e32 v6, v6, v6
	s_waitcnt lgkmcnt(0)
	v_max_f32_e32 v5, v5, v5
	v_max_f32_e32 v2, v2, v5
	v_xor_b32_e32 v5, 8, v214
	v_cmp_lt_i32_e32 vcc, v5, v4
	v_max_f32_e32 v3, v3, v6
	s_nop 0
	v_cndmask_b32_e32 v5, v214, v5, vcc
	v_lshlrev_b32_e32 v174, 2, v5
	ds_bpermute_b32 v5, v174, v3
	s_waitcnt lgkmcnt(0)
	v_max_f32_e32 v5, v5, v5
	v_max_f32_e32 v3, v3, v5
	ds_bpermute_b32 v5, v174, v2
	s_waitcnt lgkmcnt(0)
	v_max_f32_e32 v5, v5, v5
	v_max_f32_e32 v2, v2, v5
	v_xor_b32_e32 v5, 4, v214
	v_cmp_lt_i32_e32 vcc, v5, v4
	s_nop 1
	v_cndmask_b32_e32 v5, v214, v5, vcc
	v_lshlrev_b32_e32 v175, 2, v5
	ds_bpermute_b32 v5, v175, v3
	s_waitcnt lgkmcnt(0)
	v_max_f32_e32 v5, v5, v5
	v_max_f32_e32 v3, v3, v5
	ds_bpermute_b32 v5, v175, v2
	s_waitcnt lgkmcnt(0)
	v_max_f32_e32 v5, v5, v5
	v_max_f32_e32 v5, v2, v5
	v_xor_b32_e32 v2, 2, v214
	v_cmp_lt_i32_e32 vcc, v2, v4
	s_nop 1
	v_cndmask_b32_e32 v2, v214, v2, vcc
	v_lshlrev_b32_e32 v176, 2, v2
	ds_bpermute_b32 v2, v176, v3
	s_waitcnt lgkmcnt(0)
	v_max_f32_e32 v2, v2, v2
	v_max_f32_e32 v2, v3, v2
	ds_bpermute_b32 v3, v176, v5
	s_waitcnt lgkmcnt(0)
	v_max_f32_e32 v3, v3, v3
	v_max_f32_e32 v3, v5, v3
	v_xor_b32_e32 v5, 1, v214
	v_cmp_lt_i32_e32 vcc, v5, v4
	s_nop 1
	v_cndmask_b32_e32 v4, v214, v5, vcc
	v_lshlrev_b32_e32 v177, 2, v4
	ds_bpermute_b32 v4, v177, v2
	ds_bpermute_b32 v5, v177, v3
	s_cbranch_scc0 .LBB0_1067
	s_waitcnt lgkmcnt(1)
	v_max_f32_e32 v4, v4, v4
	v_max_f32_e32 v2, v2, v2
	s_waitcnt lgkmcnt(0)
	v_max_f32_e32 v5, v5, v5
	v_max_f32_e32 v3, v3, v3
	v_max_f32_e32 v2, v2, v4
	v_max_f32_e32 v3, v3, v5
	v_mul_f32_e32 v2, 0x413504f3, v2
	v_mul_f32_e32 v2, v3, v2
	v_mul_f32_e32 v2, 0x3fb8aa3b, v2
	v_mul_f32_e32 v16, 0xbf8147ae, v2
	v_ashrrev_i32_e32 v2, 1, v0
	s_movk_i32 s0, 0xffe0
	v_bfi_b32 v171, s0, v2, v0
	v_lshrrev_b32_e32 v0, 2, v0
	v_readlane_b32 s0, v252, 31
	v_and_b32_e32 v0, 8, v0
	v_readlane_b32 s1, v252, 32
	v_mov_b32_e32 v17, v16
	v_mov_b32_e32 v18, v16
	v_mov_b32_e32 v19, v16
	v_mov_b32_e32 v20, v16
	v_mov_b32_e32 v21, v16
	v_mov_b32_e32 v22, v16
	v_mov_b32_e32 v23, v16
	v_mov_b32_e32 v24, v16
	v_mov_b32_e32 v25, v16
	v_mov_b32_e32 v26, v16
	v_mov_b32_e32 v27, v16
	v_mov_b32_e32 v28, v16
	v_mov_b32_e32 v29, v16
	v_mov_b32_e32 v30, v16
	v_mov_b32_e32 v31, v16
	v_lshl_add_u64 v[160:161], s[0:1], 0, v[0:1]

.LBB0_1067:
	s_setprio 0
	s_waitcnt vmcnt(0)
	s_waitcnt lgkmcnt(0)
	s_barrier
	s_mov_b64 s[0:1], exec
	v_readlane_b32 s2, v250, 15
	v_readlane_b32 s3, v250, 16
	s_and_b64 s[2:3], s[0:1], s[2:3]
	s_xor_b64 s[0:1], s[2:3], s[0:1]
	s_mov_b64 exec, s[2:3]
	s_cbranch_execz .LBB0_1120
	v_mov_b32_e32 v0, 0x21400
	s_getreg_b32 s2, hwreg(HW_REG_XCC_ID, 0, 4)
	s_waitcnt vmcnt(0) expcnt(0) lgkmcnt(0)
	ds_read_b32 v3, v0
	ds_read_b32 v2, v207
	s_and_b32 s8, s2, 15
	s_waitcnt lgkmcnt(1)
	v_cmp_ne_u32_e32 vcc, 0, v3
	s_cbranch_vccnz .LBB0_1083
	s_mov_b32 s9, 1
	s_branch .LBB0_1071

.LBB0_1346:
	s_or_b64 exec, exec, s[0:1]
	v_mov_b32_e32 v0, v205
	s_waitcnt lgkmcnt(0)
	s_barrier
	v_readlane_b32 s0, v250, 19
	v_and_or_b32 v2, v0, 63, s20
	v_lshlrev_b32_e32 v6, 2, v2
	v_readlane_b32 s12, v250, 31
	v_readlane_b32 s13, v250, 32
	v_readlane_b32 s14, v250, 33
	v_readlane_b32 s15, v250, 34
	s_nop 2
	global_load_dword v2, v6, s[12:13]
	s_nop 0
	global_load_dword v3, v6, s[14:15]
	global_load_dword v5, v6, s[64:65]
	global_load_dword v7, v6, s[66:67]
	v_and_b32_e32 v9, 64, v214
	v_add_u32_e32 v9, 64, v9
	v_xor_b32_e32 v10, 32, v214
	v_cmp_lt_i32_e32 vcc, v10, v9
	v_readlane_b32 s8, v250, 27
	v_readlane_b32 s9, v250, 28
	v_cndmask_b32_e32 v10, v214, v10, vcc
	v_lshlrev_b32_e32 v192, 2, v10
	v_readlane_b32 s10, v250, 29
	v_readlane_b32 s11, v250, 30
	v_readlane_b32 s1, v250, 20
	v_readfirstlane_b32 s0, v204
	s_lshr_b32 s0, s0, 8
	v_readlane_b32 s1, v250, 43
	s_add_i32 s26, s0, s1
	s_and_b32 s0, s26, 1
	s_bfe_u32 s1, s26, 0x30004
	s_lshl_b32 s1, s1, 1
	s_or_b32 s0, s0, s1
	s_bfe_u32 s1, s26, 0x10001
	s_lshl_b32 s1, s1, 6
	s_or_b32 s0, s0, s1
	s_bfe_u32 s1, s26, 0x20007
	s_lshl_b32 s1, s1, 4
	s_or_b32 s0, s0, s1
	s_bfe_u32 s1, s26, 0x20002
	s_lshl_b32 s1, s1, 7
	s_or_b32 s26, s0, s1
	s_bitcmp1_b32 s26, 0
	s_cbranch_scc0 .Lprio_skip_A
	s_setprio 1
.Lprio_skip_A:
	s_cmpk_lt_i32 s26, 0x200
	v_readlane_b32 s2, v250, 21
	v_readlane_b32 s3, v250, 22
	v_readlane_b32 s4, v250, 23
	v_readlane_b32 s5, v250, 24
	v_readlane_b32 s6, v250, 25
	v_readlane_b32 s7, v250, 26
	s_waitcnt vmcnt(0)
	v_mul_f32_e32 v4, v2, v3
	ds_bpermute_b32 v4, v192, v4
	v_mul_f32_e32 v8, v5, v7
	s_waitcnt lgkmcnt(0)
	v_fmac_f32_e32 v4, v2, v3
	ds_bpermute_b32 v2, v192, v8
	global_load_dword v8, v6, s[8:9]
	v_xor_b32_e32 v3, 16, v214
	global_load_dword v6, v6, s[10:11]
	v_cmp_lt_i32_e32 vcc, v3, v9
	s_waitcnt lgkmcnt(0)
	v_fmac_f32_e32 v2, v5, v7
	s_waitcnt vmcnt(0)
	v_and_b32_e32 v10, 0x7fffffff, v6
	v_cndmask_b32_e32 v3, v214, v3, vcc
	v_lshlrev_b32_e32 v7, 2, v3
	ds_bpermute_b32 v3, v7, v4
	v_max_f32_e64 v6, |v6|, |v6|
	s_waitcnt lgkmcnt(0)
	v_add_f32_e32 v3, v4, v3
	ds_bpermute_b32 v4, v7, v2
	s_waitcnt lgkmcnt(0)
	v_add_f32_e32 v2, v2, v4
	v_xor_b32_e32 v4, 8, v214
	v_cmp_lt_i32_e32 vcc, v4, v9
	s_nop 1
	v_cndmask_b32_e32 v4, v214, v4, vcc
	v_lshlrev_b32_e32 v188, 2, v4
	ds_bpermute_b32 v4, v188, v3
	s_waitcnt lgkmcnt(0)
	v_add_f32_e32 v3, v3, v4
	ds_bpermute_b32 v4, v188, v2
	s_waitcnt lgkmcnt(0)
	v_add_f32_e32 v2, v2, v4
	v_xor_b32_e32 v4, 4, v214
	v_cmp_lt_i32_e32 vcc, v4, v9
	s_nop 1
	v_cndmask_b32_e32 v4, v214, v4, vcc
	v_lshlrev_b32_e32 v189, 2, v4
	ds_bpermute_b32 v4, v189, v3
	s_waitcnt lgkmcnt(0)
	v_add_f32_e32 v3, v3, v4
	ds_bpermute_b32 v4, v189, v2
	s_waitcnt lgkmcnt(0)
	v_add_f32_e32 v2, v2, v4
	v_xor_b32_e32 v4, 2, v214
	v_cmp_lt_i32_e32 vcc, v4, v9
	s_nop 1
	v_cndmask_b32_e32 v4, v214, v4, vcc
	v_lshlrev_b32_e32 v190, 2, v4
	ds_bpermute_b32 v4, v190, v3
	s_waitcnt lgkmcnt(0)
	v_add_f32_e32 v4, v3, v4
	ds_bpermute_b32 v3, v190, v2
	s_waitcnt lgkmcnt(0)
	v_add_f32_e32 v2, v2, v3
	v_xor_b32_e32 v3, 1, v214
	v_cmp_lt_i32_e32 vcc, v3, v9
	v_and_b32_e32 v9, 0x7fffffff, v8
	ds_bpermute_b32 v9, v192, v9
	v_max_f32_e64 v8, |v8|, |v8|
	v_cndmask_b32_e32 v3, v214, v3, vcc
	v_lshlrev_b32_e32 v191, 2, v3
	ds_bpermute_b32 v5, v191, v4
	s_waitcnt lgkmcnt(1)
	v_max_f32_e32 v9, v9, v9
	v_max_f32_e32 v8, v8, v9
	ds_bpermute_b32 v9, v192, v10
	ds_bpermute_b32 v3, v191, v2
	s_waitcnt lgkmcnt(1)
	v_max_f32_e32 v9, v9, v9
	v_max_f32_e32 v6, v6, v9
	ds_bpermute_b32 v9, v7, v8
	ds_bpermute_b32 v7, v7, v6
	s_waitcnt lgkmcnt(1)
	v_max_f32_e32 v9, v9, v9
	v_max_f32_e32 v8, v8, v9
	s_waitcnt lgkmcnt(0)
	v_max_f32_e32 v7, v7, v7
	v_max_f32_e32 v6, v6, v7
	ds_bpermute_b32 v7, v188, v8
	s_waitcnt lgkmcnt(0)
	v_max_f32_e32 v7, v7, v7
	v_max_f32_e32 v7, v8, v7
	ds_bpermute_b32 v8, v188, v6
	s_waitcnt lgkmcnt(0)
	v_max_f32_e32 v8, v8, v8
	v_max_f32_e32 v6, v6, v8
	ds_bpermute_b32 v8, v189, v7
	s_waitcnt lgkmcnt(0)
	v_max_f32_e32 v8, v8, v8
	v_max_f32_e32 v7, v7, v8
	ds_bpermute_b32 v8, v189, v6
	s_waitcnt lgkmcnt(0)
	v_max_f32_e32 v8, v8, v8
	v_max_f32_e32 v8, v6, v8
	ds_bpermute_b32 v6, v190, v7
	s_waitcnt lgkmcnt(0)
	v_max_f32_e32 v6, v6, v6
	v_max_f32_e32 v6, v7, v6
	ds_bpermute_b32 v7, v190, v8
	s_waitcnt lgkmcnt(0)
	v_max_f32_e32 v7, v7, v7
	v_max_f32_e32 v8, v8, v7
	ds_bpermute_b32 v7, v191, v6
	ds_bpermute_b32 v9, v191, v8
	s_cbranch_scc0 .LBB0_1435
	v_add_f32_e32 v4, v4, v5
	v_mul_f32_e32 v5, 0x3fb8aa3b, v4
	s_mov_b32 s0, 0x3fb8aa3b
	v_fma_f32 v10, v4, s0, -v5
	v_rndne_f32_e32 v11, v5
	v_fmac_f32_e32 v10, 0x32a5705f, v4
	v_sub_f32_e32 v5, v5, v11
	v_add_f32_e32 v5, v5, v10
	v_exp_f32_e32 v5, v5
	v_cvt_i32_f32_e32 v10, v11
	v_readlane_b32 s2, v251, 48
	v_add_f32_e32 v2, v2, v3
	v_mov_b32_e32 v11, 0x3f0e59d5
	v_mov_b32_e32 v12, 0x3e4ccccd
	v_readlane_b32 s3, v251, 49
	v_ldexp_f32 v3, v5, v10
	v_mul_f32_e32 v5, 0x3fb8aa3b, v2
	v_cndmask_b32_e64 v11, v11, v12, s[2:3]
	v_fma_f32 v10, v2, s0, -v5
	v_rndne_f32_e32 v12, v5
	v_fmac_f32_e32 v10, 0x32a5705f, v2
	v_sub_f32_e32 v5, v5, v12
	v_add_f32_e32 v5, v5, v10
	v_exp_f32_e32 v5, v5
	v_cvt_i32_f32_e32 v10, v12
	s_mov_b32 s0, 0xc2ce8ed0
	v_cmp_ngt_f32_e32 vcc, s0, v4
	s_mov_b32 s1, 0x42b17218
	v_mov_b32_e32 v12, 0x7f800000
	v_cndmask_b32_e32 v3, 0, v3, vcc
	v_cmp_nlt_f32_e32 vcc, s1, v4
	v_ldexp_f32 v4, v5, v10
	s_movk_i32 s2, 0xffe0
	v_cndmask_b32_e32 v3, v12, v3, vcc
	v_cmp_ngt_f32_e32 vcc, s0, v2
	v_sub_f32_e32 v193, 1.0, v11
	s_nop 0
	v_cndmask_b32_e32 v4, 0, v4, vcc
	v_cmp_nlt_f32_e32 vcc, s1, v2
	v_readlane_b32 s0, v251, 45
	v_readlane_b32 s1, v251, 46
	v_cndmask_b32_e32 v2, v12, v4, vcc
	v_sub_f32_e32 v2, v3, v2
	v_add_f32_e32 v176, v11, v2
	s_waitcnt lgkmcnt(0)
	v_max_f32_e32 v2, v9, v9
	v_max_f32_e32 v3, v8, v8
	v_max_f32_e32 v2, v3, v2
	v_max_f32_e32 v3, v7, v7
	v_max_f32_e32 v4, v6, v6
	v_max_f32_e32 v3, v4, v3
	v_mul_f32_e32 v3, 0x41000000, v3
	v_mul_f32_e32 v2, v2, v3
	v_mul_f32_e32 v2, 0x3fb8aa3b, v2
	s_and_b64 s[0:1], s[0:1], exec
	v_mul_f32_e32 v16, 0xbf8147ae, v2
	v_ashrrev_i32_e32 v2, 1, v0
	s_cselect_b32 s0, 0x200, 0
	v_bfi_b32 v194, s2, v2, v0
	v_lshrrev_b32_e32 v0, 3, v0
	s_add_u32 s0, s68, s0
	v_and_b32_e32 v2, 4, v0
	s_addc_u32 s1, s69, 0
	v_lshlrev_b32_e32 v0, 2, v2
	v_lshl_add_u64 v[178:179], s[0:1], 0, v[0:1]
	v_readlane_b32 s0, v252, 31
	v_lshlrev_b32_e32 v0, 1, v2
	v_readlane_b32 s1, v252, 32
	v_mov_b32_e32 v17, v16
	v_mov_b32_e32 v18, v16
	v_mov_b32_e32 v19, v16
	v_mov_b32_e32 v20, v16
	v_mov_b32_e32 v21, v16
	v_mov_b32_e32 v22, v16
	v_mov_b32_e32 v23, v16
	v_mov_b32_e32 v24, v16
	v_mov_b32_e32 v25, v16
	v_mov_b32_e32 v26, v16
	v_mov_b32_e32 v27, v16
	v_mov_b32_e32 v28, v16
	v_mov_b32_e32 v29, v16
	v_mov_b32_e32 v30, v16
	v_mov_b32_e32 v31, v16
	v_mov_b32_e32 v177, v176
	v_lshl_add_u64 v[180:181], s[0:1], 0, v[0:1]
	s_branch .LBB0_1349

.LBB0_1435:
	s_setprio 0
	s_waitcnt vmcnt(0)
	s_mov_b32 s20, s81
	s_waitcnt lgkmcnt(0)
	s_barrier
	s_mov_b64 s[0:1], exec
	v_readlane_b32 s2, v250, 15
	v_readlane_b32 s3, v250, 16
	s_and_b64 s[2:3], s[0:1], s[2:3]
	s_xor_b64 s[0:1], s[2:3], s[0:1]
	s_mov_b64 exec, s[2:3]
	s_cbranch_execz .LBB0_1505
	v_mov_b32_e32 v0, 0x21400
	s_getreg_b32 s2, hwreg(HW_REG_XCC_ID, 0, 4)
	s_waitcnt vmcnt(0) expcnt(0) lgkmcnt(0)
	ds_read_b32 v3, v0
	ds_read_b32 v2, v207
	s_and_b32 s8, s2, 15
	s_waitcnt lgkmcnt(1)
	v_cmp_ne_u32_e32 vcc, 0, v3
	s_cbranch_vccnz .LBB0_1451
	s_mov_b32 s9, 1
	s_branch .LBB0_1439
